# v48 + W1 GEMM loop with merged phase pairs (8 barriers per K-iteration, 32 MFMAs per hand-off)
# baseline (speedup 1.0000x reference)
.LBB0_749:
	s_add_u32 s20, s18, 0xfff80080
	s_addc_u32 s21, s19, -1
	s_add_i32 s58, 0, 0x10000
	v_add_u32_e32 v159, s58, v1
	ds_read_b128 v[160:163], v159
	ds_read_b128 v[164:167], v159 offset:1024
	ds_read_b128 v[168:171], v159 offset:2048
	ds_read_b128 v[172:175], v159 offset:3072
	s_cmp_eq_u32 s57, 28
	s_cselect_b32 s23, s39, s21
	s_cselect_b32 s22, s53, s20
	s_cselect_b32 s21, s31, s56
	s_cselect_b32 s20, s54, s55
	v_lshl_add_u64 v[212:213], s[18:19], 0, v[154:155]
	s_add_i32 m0, s44, 0xc000
	ds_read_b128 v[176:179], v158
	ds_read_b128 v[192:195], v158 offset:1024
	ds_read_b128 v[196:199], v158 offset:2048
	ds_read_b128 v[200:203], v158 offset:3072
	ds_read_b128 v[204:207], v158 offset:4096
	ds_read_b128 v[208:211], v158 offset:5120
	ds_read_b128 v[224:227], v158 offset:6144
	ds_read_b128 v[228:231], v158 offset:7168
	global_load_lds_dwordx4 v[212:213], off
	v_lshl_add_u64 v[212:213], s[18:19], 0, v[156:157]
	s_add_i32 m0, s44, 0xe000
	s_nop 0
	global_load_lds_dwordx4 v[212:213], off
	s_add_i32 s82, 0, 0x14000
	v_add_u32_e32 v159, s82, v1
	ds_read_b128 v[232:235], v159
	ds_read_b128 v[236:239], v159 offset:1024
	ds_read_b128 v[240:243], v159 offset:2048
	ds_read_b128 v[244:247], v159 offset:3072
	s_waitcnt vmcnt(8)
	s_waitcnt lgkmcnt(0)
	s_barrier
	v_mfma_f32_16x16x32_bf16 v[126:129], v[160:163], v[176:179], v[126:129]
	v_mfma_f32_16x16x32_bf16 v[122:125], v[168:171], v[176:179], v[122:125]
	v_mfma_f32_16x16x32_bf16 v[110:113], v[160:163], v[196:199], v[110:113]
	v_mfma_f32_16x16x32_bf16 v[106:109], v[168:171], v[196:199], v[106:109]
	v_mfma_f32_16x16x32_bf16 v[94:97], v[160:163], v[204:207], v[94:97]
	v_mfma_f32_16x16x32_bf16 v[90:93], v[168:171], v[204:207], v[90:93]
	v_mfma_f32_16x16x32_bf16 v[78:81], v[160:163], v[224:227], v[78:81]
	v_mfma_f32_16x16x32_bf16 v[74:77], v[168:171], v[224:227], v[74:77]
	v_mfma_f32_16x16x32_bf16 v[126:129], v[164:167], v[192:195], v[126:129]
	v_mfma_f32_16x16x32_bf16 v[122:125], v[172:175], v[192:195], v[122:125]
	v_mfma_f32_16x16x32_bf16 v[110:113], v[164:167], v[200:203], v[110:113]
	v_mfma_f32_16x16x32_bf16 v[106:109], v[172:175], v[200:203], v[106:109]
	v_mfma_f32_16x16x32_bf16 v[94:97], v[164:167], v[208:211], v[94:97]
	v_mfma_f32_16x16x32_bf16 v[90:93], v[172:175], v[208:211], v[90:93]
	v_mfma_f32_16x16x32_bf16 v[78:81], v[164:167], v[228:231], v[78:81]
	v_mfma_f32_16x16x32_bf16 v[74:77], v[172:175], v[228:231], v[74:77]
	v_mfma_f32_16x16x32_bf16 v[118:121], v[232:235], v[176:179], v[118:121]
	v_mfma_f32_16x16x32_bf16 v[114:117], v[240:243], v[176:179], v[114:117]
	v_mfma_f32_16x16x32_bf16 v[102:105], v[232:235], v[196:199], v[102:105]
	v_mfma_f32_16x16x32_bf16 v[98:101], v[240:243], v[196:199], v[98:101]
	v_mfma_f32_16x16x32_bf16 v[86:89], v[232:235], v[204:207], v[86:89]
	v_mfma_f32_16x16x32_bf16 v[82:85], v[240:243], v[204:207], v[82:85]
	v_mfma_f32_16x16x32_bf16 v[70:73], v[232:235], v[224:227], v[70:73]
	v_mfma_f32_16x16x32_bf16 v[66:69], v[240:243], v[224:227], v[66:69]
	v_mfma_f32_16x16x32_bf16 v[118:121], v[236:239], v[192:195], v[118:121]
	v_mfma_f32_16x16x32_bf16 v[114:117], v[244:247], v[192:195], v[114:117]
	v_mfma_f32_16x16x32_bf16 v[102:105], v[236:239], v[200:203], v[102:105]
	v_mfma_f32_16x16x32_bf16 v[98:101], v[244:247], v[200:203], v[98:101]
	v_mfma_f32_16x16x32_bf16 v[86:89], v[236:239], v[208:211], v[86:89]
	v_mfma_f32_16x16x32_bf16 v[82:85], v[244:247], v[208:211], v[82:85]
	v_mfma_f32_16x16x32_bf16 v[70:73], v[236:239], v[228:231], v[70:73]
	v_mfma_f32_16x16x32_bf16 v[66:69], v[244:247], v[228:231], v[66:69]
	s_mov_b32 m0, s44
	v_lshl_add_u64 v[250:251], s[22:23], 0, v[136:137]
	s_barrier
	ds_read_b128 v[176:179], v158 offset:16384
	ds_read_b128 v[192:195], v158 offset:17408
	ds_read_b128 v[196:199], v158 offset:18432
	ds_read_b128 v[200:203], v158 offset:19456
	ds_read_b128 v[204:207], v158 offset:20480
	ds_read_b128 v[208:211], v158 offset:21504
	ds_read_b128 v[224:227], v158 offset:22528
	ds_read_b128 v[228:231], v158 offset:23552
	global_load_lds_dwordx4 v[250:251], off
	v_lshl_add_u64 v[222:223], s[22:23], 0, v[132:133]
	s_mov_b32 m0, s45
	s_nop 0
	global_load_lds_dwordx4 v[222:223], off
	s_add_i32 s58, s58, s29
	v_lshl_add_u64 v[212:213], s[20:21], 0, v[134:135]
	s_mov_b32 m0, s58
	s_nop 0
	global_load_lds_dwordx4 v[212:213], off
	v_lshl_add_u64 v[248:249], s[20:21], 0, v[130:131]
	s_add_i32 m0, s58, 0x2000
	s_nop 0
	global_load_lds_dwordx4 v[248:249], off
	s_add_u32 s58, s20, 0x80000
	s_addc_u32 s59, s21, 0
	s_add_i32 s82, s82, s29
	s_mov_b32 m0, s82
	s_nop 0
	global_load_lds_dwordx4 v134, s[58:59]
	s_add_i32 m0, s82, 0x2000
	s_nop 0
	global_load_lds_dwordx4 v130, s[58:59]
	s_waitcnt vmcnt(8)
	s_waitcnt lgkmcnt(0)
	s_barrier
	v_mfma_f32_16x16x32_bf16 v[62:65], v[160:163], v[176:179], v[62:65]
	v_mfma_f32_16x16x32_bf16 v[58:61], v[168:171], v[176:179], v[58:61]
	v_mfma_f32_16x16x32_bf16 v[46:49], v[160:163], v[196:199], v[46:49]
	v_mfma_f32_16x16x32_bf16 v[42:45], v[168:171], v[196:199], v[42:45]
	v_mfma_f32_16x16x32_bf16 v[30:33], v[160:163], v[204:207], v[30:33]
	v_mfma_f32_16x16x32_bf16 v[26:29], v[168:171], v[204:207], v[26:29]
	v_mfma_f32_16x16x32_bf16 v[14:17], v[160:163], v[224:227], v[14:17]
	v_mfma_f32_16x16x32_bf16 v[10:13], v[168:171], v[224:227], v[10:13]
	v_mfma_f32_16x16x32_bf16 v[62:65], v[164:167], v[192:195], v[62:65]
	v_mfma_f32_16x16x32_bf16 v[58:61], v[172:175], v[192:195], v[58:61]
	v_mfma_f32_16x16x32_bf16 v[46:49], v[164:167], v[200:203], v[46:49]
	v_mfma_f32_16x16x32_bf16 v[42:45], v[172:175], v[200:203], v[42:45]
	v_mfma_f32_16x16x32_bf16 v[30:33], v[164:167], v[208:211], v[30:33]
	v_mfma_f32_16x16x32_bf16 v[26:29], v[172:175], v[208:211], v[26:29]
	v_mfma_f32_16x16x32_bf16 v[14:17], v[164:167], v[228:231], v[14:17]
	v_mfma_f32_16x16x32_bf16 v[10:13], v[172:175], v[228:231], v[10:13]
	v_mfma_f32_16x16x32_bf16 v[54:57], v[232:235], v[176:179], v[54:57]
	v_mfma_f32_16x16x32_bf16 v[50:53], v[240:243], v[176:179], v[50:53]
	v_mfma_f32_16x16x32_bf16 v[38:41], v[232:235], v[196:199], v[38:41]
	v_mfma_f32_16x16x32_bf16 v[34:37], v[240:243], v[196:199], v[34:37]
	v_mfma_f32_16x16x32_bf16 v[22:25], v[232:235], v[204:207], v[22:25]
	v_mfma_f32_16x16x32_bf16 v[18:21], v[240:243], v[204:207], v[18:21]
	v_mfma_f32_16x16x32_bf16 v[6:9], v[232:235], v[224:227], v[6:9]
	v_mfma_f32_16x16x32_bf16 v[2:5], v[240:243], v[224:227], v[2:5]
	v_mfma_f32_16x16x32_bf16 v[54:57], v[236:239], v[192:195], v[54:57]
	v_mfma_f32_16x16x32_bf16 v[50:53], v[244:247], v[192:195], v[50:53]
	v_mfma_f32_16x16x32_bf16 v[38:41], v[236:239], v[200:203], v[38:41]
	v_mfma_f32_16x16x32_bf16 v[34:37], v[244:247], v[200:203], v[34:37]
	v_mfma_f32_16x16x32_bf16 v[22:25], v[236:239], v[208:211], v[22:25]
	v_mfma_f32_16x16x32_bf16 v[18:21], v[244:247], v[208:211], v[18:21]
	v_mfma_f32_16x16x32_bf16 v[6:9], v[236:239], v[228:231], v[6:9]
	v_mfma_f32_16x16x32_bf16 v[2:5], v[244:247], v[228:231], v[2:5]
	s_add_i32 s58, 0, 0x18000
	v_add_u32_e32 v159, s58, v1
	s_barrier
	ds_read_b128 v[160:163], v159
	ds_read_b128 v[164:167], v159 offset:1024
	ds_read_b128 v[168:171], v159 offset:2048
	ds_read_b128 v[172:175], v159 offset:3072
	s_add_u32 s22, s22, 0x80000
	s_addc_u32 s23, s23, 0
	s_mov_b32 m0, s46
	v_lshl_add_u64 v[232:233], s[22:23], 0, v[136:137]
	ds_read_b128 v[176:179], v158 offset:32768
	ds_read_b128 v[192:195], v158 offset:33792
	ds_read_b128 v[196:199], v158 offset:34816
	ds_read_b128 v[200:203], v158 offset:35840
	ds_read_b128 v[204:207], v158 offset:36864
	ds_read_b128 v[208:211], v158 offset:37888
	ds_read_b128 v[224:227], v158 offset:38912
	ds_read_b128 v[228:231], v158 offset:39936
	global_load_lds_dwordx4 v[232:233], off
	v_lshl_add_u64 v[232:233], s[22:23], 0, v[132:133]
	s_mov_b32 m0, s47
	s_nop 0
	global_load_lds_dwordx4 v[232:233], off
	s_add_i32 s22, 0, 0x1c000
	s_add_i32 s23, s58, s29
	v_add_u32_e32 v159, s22, v1
	ds_read_b128 v[232:235], v159
	ds_read_b128 v[236:239], v159 offset:1024
	ds_read_b128 v[240:243], v159 offset:2048
	ds_read_b128 v[244:247], v159 offset:3072
	s_waitcnt vmcnt(8)
	s_waitcnt lgkmcnt(0)
	s_barrier
	v_mfma_f32_16x16x32_bf16 v[126:129], v[160:163], v[176:179], v[126:129]
	v_mfma_f32_16x16x32_bf16 v[122:125], v[168:171], v[176:179], v[122:125]
	v_mfma_f32_16x16x32_bf16 v[110:113], v[160:163], v[196:199], v[110:113]
	v_mfma_f32_16x16x32_bf16 v[106:109], v[168:171], v[196:199], v[106:109]
	v_mfma_f32_16x16x32_bf16 v[94:97], v[160:163], v[204:207], v[94:97]
	v_mfma_f32_16x16x32_bf16 v[90:93], v[168:171], v[204:207], v[90:93]
	v_mfma_f32_16x16x32_bf16 v[78:81], v[160:163], v[224:227], v[78:81]
	v_mfma_f32_16x16x32_bf16 v[74:77], v[168:171], v[224:227], v[74:77]
	v_mfma_f32_16x16x32_bf16 v[126:129], v[164:167], v[192:195], v[126:129]
	v_mfma_f32_16x16x32_bf16 v[122:125], v[172:175], v[192:195], v[122:125]
	v_mfma_f32_16x16x32_bf16 v[110:113], v[164:167], v[200:203], v[110:113]
	v_mfma_f32_16x16x32_bf16 v[106:109], v[172:175], v[200:203], v[106:109]
	v_mfma_f32_16x16x32_bf16 v[94:97], v[164:167], v[208:211], v[94:97]
	v_mfma_f32_16x16x32_bf16 v[90:93], v[172:175], v[208:211], v[90:93]
	v_mfma_f32_16x16x32_bf16 v[78:81], v[164:167], v[228:231], v[78:81]
	v_mfma_f32_16x16x32_bf16 v[74:77], v[172:175], v[228:231], v[74:77]
	v_mfma_f32_16x16x32_bf16 v[118:121], v[232:235], v[176:179], v[118:121]
	v_mfma_f32_16x16x32_bf16 v[114:117], v[240:243], v[176:179], v[114:117]
	v_mfma_f32_16x16x32_bf16 v[102:105], v[232:235], v[196:199], v[102:105]
	v_mfma_f32_16x16x32_bf16 v[98:101], v[240:243], v[196:199], v[98:101]
	v_mfma_f32_16x16x32_bf16 v[86:89], v[232:235], v[204:207], v[86:89]
	v_mfma_f32_16x16x32_bf16 v[82:85], v[240:243], v[204:207], v[82:85]
	v_mfma_f32_16x16x32_bf16 v[70:73], v[232:235], v[224:227], v[70:73]
	v_mfma_f32_16x16x32_bf16 v[66:69], v[240:243], v[224:227], v[66:69]
	v_mfma_f32_16x16x32_bf16 v[118:121], v[236:239], v[192:195], v[118:121]
	v_mfma_f32_16x16x32_bf16 v[114:117], v[244:247], v[192:195], v[114:117]
	v_mfma_f32_16x16x32_bf16 v[102:105], v[236:239], v[200:203], v[102:105]
	v_mfma_f32_16x16x32_bf16 v[98:101], v[244:247], v[200:203], v[98:101]
	v_mfma_f32_16x16x32_bf16 v[86:89], v[236:239], v[208:211], v[86:89]
	v_mfma_f32_16x16x32_bf16 v[82:85], v[244:247], v[208:211], v[82:85]
	v_mfma_f32_16x16x32_bf16 v[70:73], v[236:239], v[228:231], v[70:73]
	v_mfma_f32_16x16x32_bf16 v[66:69], v[244:247], v[228:231], v[66:69]
	s_mov_b32 m0, s48
	v_lshl_add_u64 v[250:251], v[250:251], 0, s[78:79]
	s_barrier
	ds_read_b128 v[176:179], v158 offset:49152
	ds_read_b128 v[192:195], v158 offset:50176
	ds_read_b128 v[196:199], v158 offset:51200
	ds_read_b128 v[200:203], v158 offset:52224
	ds_read_b128 v[204:207], v158 offset:53248
	ds_read_b128 v[208:211], v158 offset:54272
	ds_read_b128 v[224:227], v158 offset:55296
	ds_read_b128 v[228:231], v158 offset:56320
	global_load_lds_dwordx4 v[250:251], off
	v_lshl_add_u64 v[222:223], v[222:223], 0, s[78:79]
	s_mov_b32 m0, s49
	s_nop 0
	global_load_lds_dwordx4 v[222:223], off
	v_lshl_add_u64 v[212:213], v[212:213], 0, s[78:79]
	s_mov_b32 m0, s23
	s_nop 0
	global_load_lds_dwordx4 v[212:213], off
	v_lshl_add_u64 v[212:213], v[248:249], 0, s[78:79]
	s_add_i32 m0, s23, 0x2000
	s_nop 0
	global_load_lds_dwordx4 v[212:213], off
	s_add_u32 s20, s20, 0x80080
	s_addc_u32 s21, s21, 0
	s_add_i32 s22, s22, s29
	s_mov_b32 m0, s22
	s_nop 0
	global_load_lds_dwordx4 v134, s[20:21]
	s_add_i32 m0, s22, 0x2000
	s_nop 0
	global_load_lds_dwordx4 v130, s[20:21]
	s_waitcnt vmcnt(8)
	s_waitcnt lgkmcnt(0)
	s_barrier
	v_mfma_f32_16x16x32_bf16 v[62:65], v[160:163], v[176:179], v[62:65]
	v_mfma_f32_16x16x32_bf16 v[58:61], v[168:171], v[176:179], v[58:61]
	v_mfma_f32_16x16x32_bf16 v[46:49], v[160:163], v[196:199], v[46:49]
	v_mfma_f32_16x16x32_bf16 v[42:45], v[168:171], v[196:199], v[42:45]
	v_mfma_f32_16x16x32_bf16 v[30:33], v[160:163], v[204:207], v[30:33]
	v_mfma_f32_16x16x32_bf16 v[26:29], v[168:171], v[204:207], v[26:29]
	v_mfma_f32_16x16x32_bf16 v[14:17], v[160:163], v[224:227], v[14:17]
	v_mfma_f32_16x16x32_bf16 v[10:13], v[168:171], v[224:227], v[10:13]
	v_mfma_f32_16x16x32_bf16 v[62:65], v[164:167], v[192:195], v[62:65]
	v_mfma_f32_16x16x32_bf16 v[58:61], v[172:175], v[192:195], v[58:61]
	v_mfma_f32_16x16x32_bf16 v[46:49], v[164:167], v[200:203], v[46:49]
	v_mfma_f32_16x16x32_bf16 v[42:45], v[172:175], v[200:203], v[42:45]
	v_mfma_f32_16x16x32_bf16 v[30:33], v[164:167], v[208:211], v[30:33]
	v_mfma_f32_16x16x32_bf16 v[26:29], v[172:175], v[208:211], v[26:29]
	v_mfma_f32_16x16x32_bf16 v[14:17], v[164:167], v[228:231], v[14:17]
	v_mfma_f32_16x16x32_bf16 v[10:13], v[172:175], v[228:231], v[10:13]
	v_mfma_f32_16x16x32_bf16 v[54:57], v[232:235], v[176:179], v[54:57]
	v_mfma_f32_16x16x32_bf16 v[50:53], v[240:243], v[176:179], v[50:53]
	v_mfma_f32_16x16x32_bf16 v[38:41], v[232:235], v[196:199], v[38:41]
	v_mfma_f32_16x16x32_bf16 v[34:37], v[240:243], v[196:199], v[34:37]
	v_mfma_f32_16x16x32_bf16 v[22:25], v[232:235], v[204:207], v[22:25]
	v_mfma_f32_16x16x32_bf16 v[18:21], v[240:243], v[204:207], v[18:21]
	v_mfma_f32_16x16x32_bf16 v[6:9], v[232:235], v[224:227], v[6:9]
	v_mfma_f32_16x16x32_bf16 v[2:5], v[240:243], v[224:227], v[2:5]
	v_mfma_f32_16x16x32_bf16 v[54:57], v[236:239], v[192:195], v[54:57]
	v_mfma_f32_16x16x32_bf16 v[50:53], v[244:247], v[192:195], v[50:53]
	v_mfma_f32_16x16x32_bf16 v[38:41], v[236:239], v[200:203], v[38:41]
	v_mfma_f32_16x16x32_bf16 v[34:37], v[244:247], v[200:203], v[34:37]
	v_mfma_f32_16x16x32_bf16 v[22:25], v[236:239], v[208:211], v[22:25]
	v_mfma_f32_16x16x32_bf16 v[18:21], v[244:247], v[208:211], v[18:21]
	v_mfma_f32_16x16x32_bf16 v[6:9], v[236:239], v[228:231], v[6:9]
	v_mfma_f32_16x16x32_bf16 v[2:5], v[244:247], v[228:231], v[2:5]
	s_add_i32 s57, s57, 2
	s_add_u32 s18, s18, 0x100
	s_addc_u32 s19, s19, 0
	s_add_u32 s55, s55, 0x100
	s_addc_u32 s56, s56, 0
	s_cmp_gt_u32 s57, 29
	s_barrier
	s_cbranch_scc0 .LBB0_749
	s_lshl_b32 s18, s52, 5
	s_add_i32 s18, s18, s51
	v_max_f32_e32 v122, 0, v122
	v_max_f32_e32 v123, 0, v123
	s_ashr_i32 s19, s18, 31
	v_pk_mul_f32 v[162:163], v[122:123], v[122:123]
	v_max_f32_e32 v123, v124, v124
	s_lshl_b64 s[18:19], s[18:19], 17
	v_max_f32_e32 v122, v128, v128
	v_max_f32_e32 v124, 0, v123
	v_max_f32_e32 v123, v129, v129
	s_add_u32 s18, s68, s18
	v_max_f32_e32 v126, 0, v126
	v_max_f32_e32 v127, 0, v127
	v_max_f32_e32 v122, 0, v122
	v_max_f32_e32 v123, 0, v123
	v_max_f32_e32 v125, 0, v125
	s_addc_u32 s19, s69, s19
	v_pk_mul_f32 v[126:127], v[126:127], v[126:127]
	v_pk_mul_f32 v[128:129], v[122:123], v[122:123]
	v_pk_mul_f32 v[164:165], v[124:125], v[124:125]
	v_lshl_add_u64 v[160:161], v[138:139], 1, s[18:19]
	v_cvt_pk_bf16_f32 v122, v126, v127
	v_cvt_pk_bf16_f32 v123, v128, v129
	v_cvt_pk_bf16_f32 v124, v162, v163
	v_cvt_pk_bf16_f32 v125, v164, v165
	v_max_f32_e32 v114, 0, v114
	v_max_f32_e32 v115, 0, v115
	global_store_dwordx4 v[160:161], v[122:125], off
	v_max_f32_e32 v118, v118, v118
	v_max_f32_e32 v119, v119, v119
	v_pk_mul_f32 v[122:123], v[114:115], v[114:115]
	v_max_f32_e32 v115, v116, v116
	v_max_f32_e32 v114, v120, v120
	v_max_f32_e32 v116, 0, v115
	v_max_f32_e32 v115, v121, v121
	v_max_f32_e32 v118, 0, v118
	v_max_f32_e32 v119, 0, v119
	v_max_f32_e32 v114, 0, v114
	v_max_f32_e32 v115, 0, v115
	v_max_f32_e32 v117, 0, v117
	v_pk_mul_f32 v[118:119], v[118:119], v[118:119]
	v_pk_mul_f32 v[120:121], v[114:115], v[114:115]
	v_pk_mul_f32 v[124:125], v[116:117], v[116:117]
	v_cvt_pk_bf16_f32 v114, v118, v119
	v_cvt_pk_bf16_f32 v115, v120, v121
	v_cvt_pk_bf16_f32 v116, v122, v123
	v_cvt_pk_bf16_f32 v117, v124, v125
	v_max_f32_e32 v106, 0, v106
	v_max_f32_e32 v107, 0, v107
	global_store_dwordx4 v[160:161], v[114:117], off offset:256
	v_max_f32_e32 v110, v110, v110
	v_max_f32_e32 v111, v111, v111
	v_pk_mul_f32 v[116:117], v[106:107], v[106:107]
	v_max_f32_e32 v107, v108, v108
	v_max_f32_e32 v106, v112, v112
	v_max_f32_e32 v108, 0, v107
	v_max_f32_e32 v107, v113, v113
	v_max_f32_e32 v110, 0, v110
	v_max_f32_e32 v111, 0, v111
	v_max_f32_e32 v106, 0, v106
	v_max_f32_e32 v107, 0, v107
	v_max_f32_e32 v109, 0, v109
	v_pk_mul_f32 v[110:111], v[110:111], v[110:111]
	v_pk_mul_f32 v[112:113], v[106:107], v[106:107]
	v_pk_mul_f32 v[118:119], v[108:109], v[108:109]
	v_lshl_add_u64 v[114:115], v[140:141], 1, s[18:19]
	v_cvt_pk_bf16_f32 v106, v110, v111
	v_cvt_pk_bf16_f32 v107, v112, v113
	v_cvt_pk_bf16_f32 v108, v116, v117
	v_cvt_pk_bf16_f32 v109, v118, v119
	v_max_f32_e32 v98, 0, v98
	v_max_f32_e32 v99, 0, v99
	global_store_dwordx4 v[114:115], v[106:109], off
	v_max_f32_e32 v102, v102, v102
	v_max_f32_e32 v103, v103, v103
	v_pk_mul_f32 v[106:107], v[98:99], v[98:99]
	v_max_f32_e32 v99, v100, v100
	v_max_f32_e32 v98, v104, v104
	v_max_f32_e32 v100, 0, v99
	v_max_f32_e32 v99, v105, v105
	v_max_f32_e32 v102, 0, v102
	v_max_f32_e32 v103, 0, v103
	v_max_f32_e32 v98, 0, v98
	v_max_f32_e32 v99, 0, v99
	v_max_f32_e32 v101, 0, v101
	v_pk_mul_f32 v[102:103], v[102:103], v[102:103]
	v_pk_mul_f32 v[104:105], v[98:99], v[98:99]
	v_pk_mul_f32 v[108:109], v[100:101], v[100:101]
	v_cvt_pk_bf16_f32 v98, v102, v103
	v_cvt_pk_bf16_f32 v99, v104, v105
	v_cvt_pk_bf16_f32 v100, v106, v107
	v_cvt_pk_bf16_f32 v101, v108, v109
	v_max_f32_e32 v90, 0, v90
	v_max_f32_e32 v91, 0, v91
	global_store_dwordx4 v[114:115], v[98:101], off offset:256
	v_max_f32_e32 v94, v94, v94
	v_max_f32_e32 v95, v95, v95
	v_pk_mul_f32 v[100:101], v[90:91], v[90:91]
	v_max_f32_e32 v91, v92, v92
	v_max_f32_e32 v90, v96, v96
	v_max_f32_e32 v92, 0, v91
	v_max_f32_e32 v91, v97, v97
	v_max_f32_e32 v94, 0, v94
	v_max_f32_e32 v95, 0, v95
	v_max_f32_e32 v90, 0, v90
	v_max_f32_e32 v91, 0, v91
	v_max_f32_e32 v93, 0, v93
	v_pk_mul_f32 v[94:95], v[94:95], v[94:95]
	v_pk_mul_f32 v[96:97], v[90:91], v[90:91]
	v_pk_mul_f32 v[102:103], v[92:93], v[92:93]
	v_lshl_add_u64 v[98:99], v[142:143], 1, s[18:19]
	v_cvt_pk_bf16_f32 v90, v94, v95
	v_cvt_pk_bf16_f32 v91, v96, v97
	v_cvt_pk_bf16_f32 v92, v100, v101
	v_cvt_pk_bf16_f32 v93, v102, v103
	v_max_f32_e32 v82, 0, v82
	v_max_f32_e32 v83, 0, v83
	global_store_dwordx4 v[98:99], v[90:93], off
	v_max_f32_e32 v86, v86, v86
	v_max_f32_e32 v87, v87, v87
	v_pk_mul_f32 v[90:91], v[82:83], v[82:83]
	v_max_f32_e32 v83, v84, v84
	v_max_f32_e32 v82, v88, v88
	v_max_f32_e32 v84, 0, v83
	v_max_f32_e32 v83, v89, v89
	v_max_f32_e32 v86, 0, v86
	v_max_f32_e32 v87, 0, v87
	v_max_f32_e32 v82, 0, v82
	v_max_f32_e32 v83, 0, v83
	v_max_f32_e32 v85, 0, v85
	v_pk_mul_f32 v[86:87], v[86:87], v[86:87]
	v_pk_mul_f32 v[88:89], v[82:83], v[82:83]
	v_pk_mul_f32 v[92:93], v[84:85], v[84:85]
	v_cvt_pk_bf16_f32 v82, v86, v87
	v_cvt_pk_bf16_f32 v83, v88, v89
	v_cvt_pk_bf16_f32 v84, v90, v91
	v_cvt_pk_bf16_f32 v85, v92, v93
	v_max_f32_e32 v74, 0, v74
	v_max_f32_e32 v75, 0, v75
	global_store_dwordx4 v[98:99], v[82:85], off offset:256
	v_max_f32_e32 v78, v78, v78
	v_max_f32_e32 v79, v79, v79
	v_pk_mul_f32 v[84:85], v[74:75], v[74:75]
	v_max_f32_e32 v75, v76, v76
	v_max_f32_e32 v74, v80, v80
	v_max_f32_e32 v76, 0, v75
	v_max_f32_e32 v75, v81, v81
	v_max_f32_e32 v78, 0, v78
	v_max_f32_e32 v79, 0, v79
	v_max_f32_e32 v74, 0, v74
	v_max_f32_e32 v75, 0, v75
	v_max_f32_e32 v77, 0, v77
	v_pk_mul_f32 v[78:79], v[78:79], v[78:79]
	v_pk_mul_f32 v[80:81], v[74:75], v[74:75]
	v_pk_mul_f32 v[86:87], v[76:77], v[76:77]
	v_lshl_add_u64 v[82:83], v[144:145], 1, s[18:19]
	v_cvt_pk_bf16_f32 v74, v78, v79
	v_cvt_pk_bf16_f32 v75, v80, v81
	v_cvt_pk_bf16_f32 v76, v84, v85
	v_cvt_pk_bf16_f32 v77, v86, v87
	v_max_f32_e32 v66, 0, v66
	v_max_f32_e32 v67, 0, v67
	global_store_dwordx4 v[82:83], v[74:77], off
	v_max_f32_e32 v70, v70, v70
	v_max_f32_e32 v71, v71, v71
	v_pk_mul_f32 v[74:75], v[66:67], v[66:67]
	v_max_f32_e32 v67, v68, v68
	v_max_f32_e32 v66, v72, v72
	v_max_f32_e32 v68, 0, v67
	v_max_f32_e32 v67, v73, v73
	v_max_f32_e32 v70, 0, v70
	v_max_f32_e32 v71, 0, v71
	v_max_f32_e32 v66, 0, v66
	v_max_f32_e32 v67, 0, v67
	v_max_f32_e32 v69, 0, v69
	v_pk_mul_f32 v[70:71], v[70:71], v[70:71]
	v_pk_mul_f32 v[72:73], v[66:67], v[66:67]
	v_pk_mul_f32 v[76:77], v[68:69], v[68:69]
	v_cvt_pk_bf16_f32 v66, v70, v71
	v_cvt_pk_bf16_f32 v67, v72, v73
	v_cvt_pk_bf16_f32 v68, v74, v75
	v_cvt_pk_bf16_f32 v69, v76, v77
	v_max_f32_e32 v58, 0, v58
	v_max_f32_e32 v59, 0, v59
	global_store_dwordx4 v[82:83], v[66:69], off offset:256
	v_max_f32_e32 v62, v62, v62
	v_max_f32_e32 v63, v63, v63
	v_pk_mul_f32 v[68:69], v[58:59], v[58:59]
	v_max_f32_e32 v59, v60, v60
	v_max_f32_e32 v58, v64, v64
	v_max_f32_e32 v60, 0, v59
	v_max_f32_e32 v59, v65, v65
	v_max_f32_e32 v62, 0, v62
	v_max_f32_e32 v63, 0, v63
	v_max_f32_e32 v58, 0, v58
	v_max_f32_e32 v59, 0, v59
	v_max_f32_e32 v61, 0, v61
	v_pk_mul_f32 v[62:63], v[62:63], v[62:63]
	v_pk_mul_f32 v[64:65], v[58:59], v[58:59]
	v_pk_mul_f32 v[70:71], v[60:61], v[60:61]
	v_lshl_add_u64 v[66:67], v[146:147], 1, s[18:19]
	v_cvt_pk_bf16_f32 v58, v62, v63
	v_cvt_pk_bf16_f32 v59, v64, v65
	v_cvt_pk_bf16_f32 v60, v68, v69
	v_cvt_pk_bf16_f32 v61, v70, v71
	v_max_f32_e32 v50, 0, v50
	v_max_f32_e32 v51, 0, v51
	global_store_dwordx4 v[66:67], v[58:61], off
	v_max_f32_e32 v54, v54, v54
	v_max_f32_e32 v55, v55, v55
	v_pk_mul_f32 v[58:59], v[50:51], v[50:51]
	v_max_f32_e32 v51, v52, v52
	v_max_f32_e32 v50, v56, v56
	v_max_f32_e32 v52, 0, v51
	v_max_f32_e32 v51, v57, v57
	v_max_f32_e32 v54, 0, v54
	v_max_f32_e32 v55, 0, v55
	v_max_f32_e32 v50, 0, v50
	v_max_f32_e32 v51, 0, v51
	v_max_f32_e32 v53, 0, v53
	v_pk_mul_f32 v[54:55], v[54:55], v[54:55]
	v_pk_mul_f32 v[56:57], v[50:51], v[50:51]
	v_pk_mul_f32 v[60:61], v[52:53], v[52:53]
	v_cvt_pk_bf16_f32 v50, v54, v55
	v_cvt_pk_bf16_f32 v51, v56, v57
	v_cvt_pk_bf16_f32 v52, v58, v59
	v_cvt_pk_bf16_f32 v53, v60, v61
	v_max_f32_e32 v42, 0, v42
	v_max_f32_e32 v43, 0, v43
	global_store_dwordx4 v[66:67], v[50:53], off offset:256
	v_max_f32_e32 v46, v46, v46
	v_max_f32_e32 v47, v47, v47
	v_pk_mul_f32 v[52:53], v[42:43], v[42:43]
	v_max_f32_e32 v43, v44, v44
	v_max_f32_e32 v42, v48, v48
	v_max_f32_e32 v44, 0, v43
	v_max_f32_e32 v43, v49, v49
	v_max_f32_e32 v46, 0, v46
	v_max_f32_e32 v47, 0, v47
	v_max_f32_e32 v42, 0, v42
	v_max_f32_e32 v43, 0, v43
	v_max_f32_e32 v45, 0, v45
	v_pk_mul_f32 v[46:47], v[46:47], v[46:47]
	v_pk_mul_f32 v[48:49], v[42:43], v[42:43]
	v_pk_mul_f32 v[54:55], v[44:45], v[44:45]
	v_lshl_add_u64 v[50:51], v[148:149], 1, s[18:19]
	v_cvt_pk_bf16_f32 v42, v46, v47
	v_cvt_pk_bf16_f32 v43, v48, v49
	v_cvt_pk_bf16_f32 v44, v52, v53
	v_cvt_pk_bf16_f32 v45, v54, v55
	v_max_f32_e32 v34, 0, v34
	v_max_f32_e32 v35, 0, v35
	global_store_dwordx4 v[50:51], v[42:45], off
	v_max_f32_e32 v38, v38, v38
	v_max_f32_e32 v39, v39, v39
	v_pk_mul_f32 v[42:43], v[34:35], v[34:35]
	v_max_f32_e32 v35, v36, v36
	v_max_f32_e32 v34, v40, v40
	v_max_f32_e32 v36, 0, v35
	v_max_f32_e32 v35, v41, v41
	v_max_f32_e32 v38, 0, v38
	v_max_f32_e32 v39, 0, v39
	v_max_f32_e32 v34, 0, v34
	v_max_f32_e32 v35, 0, v35
	v_max_f32_e32 v37, 0, v37
	v_pk_mul_f32 v[38:39], v[38:39], v[38:39]
	v_pk_mul_f32 v[40:41], v[34:35], v[34:35]
	v_pk_mul_f32 v[44:45], v[36:37], v[36:37]
	v_cvt_pk_bf16_f32 v34, v38, v39
	v_cvt_pk_bf16_f32 v35, v40, v41
	v_cvt_pk_bf16_f32 v36, v42, v43
	v_cvt_pk_bf16_f32 v37, v44, v45
	v_max_f32_e32 v26, 0, v26
	v_max_f32_e32 v27, 0, v27
	global_store_dwordx4 v[50:51], v[34:37], off offset:256
	v_max_f32_e32 v30, v30, v30
	v_max_f32_e32 v31, v31, v31
	v_pk_mul_f32 v[36:37], v[26:27], v[26:27]
	v_max_f32_e32 v27, v28, v28
	v_max_f32_e32 v26, v32, v32
	v_max_f32_e32 v28, 0, v27
	v_max_f32_e32 v27, v33, v33
	v_max_f32_e32 v30, 0, v30
	v_max_f32_e32 v31, 0, v31
	v_max_f32_e32 v26, 0, v26
	v_max_f32_e32 v27, 0, v27
	v_max_f32_e32 v29, 0, v29
	v_pk_mul_f32 v[30:31], v[30:31], v[30:31]
	v_pk_mul_f32 v[32:33], v[26:27], v[26:27]
	v_pk_mul_f32 v[38:39], v[28:29], v[28:29]
	v_lshl_add_u64 v[34:35], v[150:151], 1, s[18:19]
	v_cvt_pk_bf16_f32 v26, v30, v31
	v_cvt_pk_bf16_f32 v27, v32, v33
	v_cvt_pk_bf16_f32 v28, v36, v37
	v_cvt_pk_bf16_f32 v29, v38, v39
	v_max_f32_e32 v18, 0, v18
	v_max_f32_e32 v19, 0, v19
	global_store_dwordx4 v[34:35], v[26:29], off
	v_max_f32_e32 v22, v22, v22
	v_max_f32_e32 v23, v23, v23
	v_pk_mul_f32 v[26:27], v[18:19], v[18:19]
	v_max_f32_e32 v19, v20, v20
	v_max_f32_e32 v18, v24, v24
	v_max_f32_e32 v20, 0, v19
	v_max_f32_e32 v19, v25, v25
	v_max_f32_e32 v22, 0, v22
	v_max_f32_e32 v23, 0, v23
	v_max_f32_e32 v18, 0, v18
	v_max_f32_e32 v19, 0, v19
	v_max_f32_e32 v21, 0, v21
	v_pk_mul_f32 v[22:23], v[22:23], v[22:23]
	v_pk_mul_f32 v[24:25], v[18:19], v[18:19]
	v_pk_mul_f32 v[28:29], v[20:21], v[20:21]
	v_cvt_pk_bf16_f32 v18, v22, v23
	v_cvt_pk_bf16_f32 v19, v24, v25
	v_cvt_pk_bf16_f32 v20, v26, v27
	v_cvt_pk_bf16_f32 v21, v28, v29
	v_max_f32_e32 v10, 0, v10
	v_max_f32_e32 v11, 0, v11
	global_store_dwordx4 v[34:35], v[18:21], off offset:256
	v_max_f32_e32 v14, v14, v14
	v_max_f32_e32 v15, v15, v15
	v_pk_mul_f32 v[20:21], v[10:11], v[10:11]
	v_max_f32_e32 v11, v12, v12
	v_max_f32_e32 v10, v16, v16
	v_max_f32_e32 v12, 0, v11
	v_max_f32_e32 v11, v17, v17
	v_max_f32_e32 v14, 0, v14
	v_max_f32_e32 v15, 0, v15
	v_max_f32_e32 v10, 0, v10
	v_max_f32_e32 v11, 0, v11
	v_max_f32_e32 v13, 0, v13
	v_pk_mul_f32 v[14:15], v[14:15], v[14:15]
	v_pk_mul_f32 v[16:17], v[10:11], v[10:11]
	v_pk_mul_f32 v[22:23], v[12:13], v[12:13]
	v_lshl_add_u64 v[18:19], v[152:153], 1, s[18:19]
	v_cvt_pk_bf16_f32 v10, v14, v15
	v_cvt_pk_bf16_f32 v11, v16, v17
	v_cvt_pk_bf16_f32 v12, v20, v21
	v_cvt_pk_bf16_f32 v13, v22, v23
	v_max_f32_e32 v2, 0, v2
	v_max_f32_e32 v3, 0, v3
	global_store_dwordx4 v[18:19], v[10:13], off
	v_max_f32_e32 v6, v6, v6
	v_max_f32_e32 v7, v7, v7
	v_pk_mul_f32 v[10:11], v[2:3], v[2:3]
	v_max_f32_e32 v3, v4, v4
	v_max_f32_e32 v2, v8, v8
	v_max_f32_e32 v4, 0, v3
	v_max_f32_e32 v3, v9, v9
	v_max_f32_e32 v6, 0, v6
	v_max_f32_e32 v7, 0, v7
	v_max_f32_e32 v2, 0, v2
	v_max_f32_e32 v3, 0, v3
	v_max_f32_e32 v5, 0, v5
	v_pk_mul_f32 v[6:7], v[6:7], v[6:7]
	v_pk_mul_f32 v[8:9], v[2:3], v[2:3]
	v_pk_mul_f32 v[12:13], v[4:5], v[4:5]
	v_cvt_pk_bf16_f32 v2, v6, v7
	v_cvt_pk_bf16_f32 v3, v8, v9
	v_cvt_pk_bf16_f32 v4, v10, v11
	v_cvt_pk_bf16_f32 v5, v12, v13
	s_and_b64 vcc, exec, s[0:1]
	s_mov_b32 s51, s30
	s_mov_b32 s52, s38
	s_mov_b64 s[20:21], s[80:81]
	s_mov_b64 s[18:19], s[42:43]
	global_store_dwordx4 v[18:19], v[2:5], off offset:256
	s_cbranch_vccz .LBB0_742
	s_waitcnt vmcnt(0)
	v_readlane_b32 s38, v255, 28
	s_cmpk_gt_u32 s26, 0xff
	v_readlane_b32 s39, v255, 29
	v_readlane_b32 s42, v255, 32
	s_cbranch_scc1 .LBB0_753
	s_barrier
